# gdnprep Q'/K'T image copy: 16-byte chunks (ds_read_b64 / gathered u16 + pack) and dwordx4 stores instead of 64 short stores per thread
# speedup vs baseline: 1.0273x; 1.0071x over previous
; DI int perm32(int x) { return ((x >> 2) & 3) * 8 + (x >> 4) * 4 + (x & 3); }
; DI void gdnprep_item(const Params& p, int item, unsigned char* ldsb) {
;     ...
;   for (int e = 0; e < 32; ++e) {
;     int idx = tid + 256 * e;
;     { int i = idx >> 7, d = idx & 127; Qp[i * 128 + (d & ~31) + perm32(d & 31)] = sQ[i * 136 + d]; }
;     { int d = idx >> 6, i = idx & 63; KTp[d * 64 + (i & ~31) + perm32(i & 31)] = sK[i * 136 + d]; }
;   }
.LBB0_448:
	s_or_b64 exec, exec, s[0:1]
	s_lshl_b64 s[4:5], s[38:39], 1
	s_add_u32 s0, s80, s4
	s_addc_u32 s1, s81, s5
	s_add_u32 s24, s82, s4
	s_movk_i32 s6, 0x110
	s_addc_u32 s25, s83, s5
	v_lshlrev_b32_e32 v2, 4, v201
	v_add_u32_e32 v64, 0x1000, v2
	v_add_u32_e32 v65, 0x2000, v2
	v_add_u32_e32 v66, 0x3000, v2
	v_lshrrev_b32_e32 v3, 4, v201
	v_and_b32_e32 v4, 15, v201
	v_lshrrev_b32_e32 v5, 2, v4
	v_and_b32_e32 v6, 3, v4
	v_mul_u32_u24_e32 v7, 0x110, v3
	v_lshl_add_u32 v7, v5, 6, v7
	v_lshl_add_u32 v7, v6, 3, v7
	ds_read_b64 v[8:9], v7 offset:17408
	ds_read_b64 v[10:11], v7 offset:17440
	ds_read_b64 v[12:13], v7 offset:21760
	ds_read_b64 v[14:15], v7 offset:21792
	ds_read_b64 v[16:17], v7 offset:26112
	ds_read_b64 v[18:19], v7 offset:26144
	ds_read_b64 v[20:21], v7 offset:30464
	ds_read_b64 v[22:23], v7 offset:30496
	v_lshrrev_b32_e32 v24, 3, v201
	v_and_b32_e32 v25, 7, v201
	v_lshrrev_b32_e32 v26, 2, v25
	v_and_b32_e32 v27, 3, v25
	v_lshlrev_b32_e32 v28, 1, v24
	v_mul_u32_u24_e32 v29, 0x2200, v26
	v_mul_u32_u24_e32 v30, 0x440, v27
	v_add3_u32 v28, v28, v29, v30
	s_waitcnt lgkmcnt(0)
	global_store_dwordx4 v2, v[8:11], s[24:25]
	global_store_dwordx4 v64, v[12:15], s[24:25]
	global_store_dwordx4 v65, v[16:19], s[24:25]
	global_store_dwordx4 v66, v[20:23], s[24:25]
	ds_read_u16 v32, v28 offset:0
	ds_read_u16 v33, v28 offset:272
	ds_read_u16 v34, v28 offset:544
	ds_read_u16 v35, v28 offset:816
	ds_read_u16 v36, v28 offset:4352
	ds_read_u16 v37, v28 offset:4624
	ds_read_u16 v38, v28 offset:4896
	ds_read_u16 v39, v28 offset:5168
	ds_read_u16 v40, v28 offset:64
	ds_read_u16 v41, v28 offset:336
	ds_read_u16 v42, v28 offset:608
	ds_read_u16 v43, v28 offset:880
	ds_read_u16 v44, v28 offset:4416
	ds_read_u16 v45, v28 offset:4688
	ds_read_u16 v46, v28 offset:4960
	s_waitcnt lgkmcnt(7)
	ds_read_u16 v47, v28 offset:5232
	v_lshl_or_b32 v48, v33, 16, v32
	v_lshl_or_b32 v49, v35, 16, v34
	v_lshl_or_b32 v50, v37, 16, v36
	v_lshl_or_b32 v51, v39, 16, v38
	global_store_dwordx4 v2, v[48:51], s[0:1]
	ds_read_u16 v32, v28 offset:128
	ds_read_u16 v33, v28 offset:400
	ds_read_u16 v34, v28 offset:672
	ds_read_u16 v35, v28 offset:944
	ds_read_u16 v36, v28 offset:4480
	ds_read_u16 v37, v28 offset:4752
	ds_read_u16 v38, v28 offset:5024
	s_waitcnt lgkmcnt(7)
	ds_read_u16 v39, v28 offset:5296
	v_lshl_or_b32 v52, v41, 16, v40
	v_lshl_or_b32 v53, v43, 16, v42
	v_lshl_or_b32 v54, v45, 16, v44
	v_lshl_or_b32 v55, v47, 16, v46
	global_store_dwordx4 v64, v[52:55], s[0:1]
	ds_read_u16 v40, v28 offset:192
	ds_read_u16 v41, v28 offset:464
	ds_read_u16 v42, v28 offset:736
	ds_read_u16 v43, v28 offset:1008
	ds_read_u16 v44, v28 offset:4544
	ds_read_u16 v45, v28 offset:4816
	ds_read_u16 v46, v28 offset:5088
	s_waitcnt lgkmcnt(7)
	ds_read_u16 v47, v28 offset:5360
	v_lshl_or_b32 v56, v33, 16, v32
	v_lshl_or_b32 v57, v35, 16, v34
	v_lshl_or_b32 v58, v37, 16, v36
	v_lshl_or_b32 v59, v39, 16, v38
	global_store_dwordx4 v65, v[56:59], s[0:1]
	s_waitcnt lgkmcnt(0)
	v_lshl_or_b32 v60, v41, 16, v40
	v_lshl_or_b32 v61, v43, 16, v42
	v_lshl_or_b32 v62, v45, 16, v44
	v_lshl_or_b32 v63, v47, 16, v46
	global_store_dwordx4 v66, v[60:63], s[0:1]
	s_waitcnt vmcnt(63) expcnt(7) lgkmcnt(15)
	s_barrier
